# C mixer: skip/rescale decision moved after 4th PV MFMA, 12 PV gaps now carry exp/sum/cvt of the current tile
# speedup vs baseline: 1.0141x; 1.0017x over previous
; #define LAS __attribute__((address_space(3)))
; __device__ __forceinline__ void attn_C_item(const bf16_t* P, bf16_t* act_c, int S, int seqbase, int q0, int h, float lam, float oml, const float* subln_g, LAS char* lds, int tid, int w, int lane) {
;     ...
;             { auto rr = __builtin_amdgcn_permlane32_swap(__float_as_uint(rm), __float_as_uint(rm), false, false); rm = fmaxf(__uint_as_float(rr[0]), __uint_as_float(rr[1])); }
;             pvalid = first || !__all(rm < -150.0f);
;             if (pvalid) {
;                 if (first || __any(rm > 8.0f)) {
;                     const float dl = first ? rm : fmaxf(rm, 0.0f); m += dl;
;                     if (!first) { const float alpha = __builtin_amdgcn_exp2f(-dl); l *= alpha;
; #pragma unroll
;                     for (int db = 0; db < 4; ++db) o[db] = o[db] * alpha; }
; #pragma unroll
;                     for (int rg = 0; rg < 16; ++rg) { s0[rg] -= dl; s1[rg] -= dl; negm[rg] = -m; }
;                 }
;                 float ps0 = 0.f, ps1 = 0.f;
; #pragma unroll
;                 for (int rg = 0; rg < 16; ++rg) { s0[rg] = __builtin_amdgcn_exp2f(s0[rg]); s1[rg] = __builtin_amdgcn_exp2f(s1[rg]); ps0 += s0[rg]; ps1 += s1[rg]; }
;                 l += ps0 + ps1;
; #pragma unroll
;                 for (int st = 0; st < 2; ++st) {
;                     u32x4 wa, wb;
;                     wa.x = cvtpk(s0[8 * st + 0], s0[8 * st + 1]); wa.y = cvtpk(s0[8 * st + 2], s0[8 * st + 3]); wa.z = cvtpk(s0[8 * st + 4], s0[8 * st + 5]); wa.w = cvtpk(s0[8 * st + 6], s0[8 * st + 7]);
;                     wb.x = cvtpk(s1[8 * st + 0], s1[8 * st + 1]); wb.y = cvtpk(s1[8 * st + 2], s1[8 * st + 3]); wb.z = cvtpk(s1[8 * st + 4], s1[8 * st + 5]); wb.w = cvtpk(s1[8 * st + 6], s1[8 * st + 7]);
;                     pf[st] = __builtin_bit_cast(bf16x8, wa); pf[2 + st] = __builtin_bit_cast(bf16x8, wb);
;                 }
;             }
;     };
;     auto pv_bm = [&](const LAS char* bufp, const int T) __attribute__((always_inline)) {
;             const LAS char* vt = bufp + C_V + troff;
;             s16x4 vlo[2][4], vhi[2][4];
;     ...
;             __builtin_amdgcn_sched_barrier(0);
;             PV_RD(0, 0); PV_RD(1, 1);
;             C_BIASMAX(T);
;             PV_MM(0, 0); PV_RD(2, 0); PV_MM(1, 1); PV_RD(3, 1); PV_MM(2, 0); PV_MM(3, 1);
;             __builtin_amdgcn_sched_group_barrier(0x100, 16, 0);
; #pragma unroll
.Lc_pv:
	s_and_b32 s12, s17, 0x18000
	v_add_u32_e32 v185, s12, v248
	ds_read_b64_tr_b16 v[94:95], v185 offset:16384
	ds_read_b64_tr_b16 v[96:97], v185 offset:16896
	ds_read_b64_tr_b16 v[208:209], v185 offset:20480
	ds_read_b64_tr_b16 v[210:211], v185 offset:20992
	ds_read_b64_tr_b16 v[82:83], v185 offset:24576
	ds_read_b64_tr_b16 v[84:85], v185 offset:25088
	ds_read_b64_tr_b16 v[100:101], v185 offset:28672
	ds_read_b64_tr_b16 v[102:103], v185 offset:29184
	ds_read_b64_tr_b16 v[86:87], v185 offset:17408
	ds_read_b64_tr_b16 v[88:89], v185 offset:17920
	ds_read_b64_tr_b16 v[108:109], v185 offset:21504
	ds_read_b64_tr_b16 v[110:111], v185 offset:22016
	ds_read_b64_tr_b16 v[104:105], v185 offset:25600
	ds_read_b64_tr_b16 v[106:107], v185 offset:26112
	ds_read_b64_tr_b16 v[90:91], v185 offset:29696
	ds_read_b64_tr_b16 v[92:93], v185 offset:30208
	s_waitcnt lgkmcnt(14)
	v_mfma_f32_32x32x16_bf16 v[48:63], v[94:97], v[172:175], v[48:63]
	v_max_f32_e32 v183, v128, v129
	v_max_f32_e32 v207, v112, v113
	v_max3_f32 v183, v183, v130, v131
	v_max3_f32 v207, v207, v114, v115
	s_waitcnt lgkmcnt(12)
	v_mfma_f32_32x32x16_bf16 v[32:47], v[208:211], v[172:175], v[32:47]
	v_max3_f32 v183, v183, v132, v133
	v_max3_f32 v207, v207, v116, v117
	v_max3_f32 v183, v183, v134, v135
	v_max3_f32 v207, v207, v118, v119
	s_waitcnt lgkmcnt(10)
	v_mfma_f32_32x32x16_bf16 v[16:31], v[82:85], v[172:175], v[16:31]
	v_max3_f32 v183, v183, v136, v137
	v_max3_f32 v207, v207, v120, v121
	v_max3_f32 v183, v183, v138, v139
	v_max3_f32 v207, v207, v122, v123
	s_waitcnt lgkmcnt(8)
	v_mfma_f32_32x32x16_bf16 v[0:15], v[100:103], v[172:175], v[0:15]
	v_max3_f32 v183, v183, v140, v141
	v_max3_f32 v207, v207, v124, v125
	v_max3_f32 v183, v183, v142, v143
	v_max3_f32 v207, v207, v126, v127
	ds_read_b64_tr_b16 v[66:67], v185 offset:18432
	ds_read_b64_tr_b16 v[68:69], v185 offset:18944
	ds_read_b64_tr_b16 v[70:71], v185 offset:22528
	ds_read_b64_tr_b16 v[72:73], v185 offset:23040
	ds_read_b64_tr_b16 v[208:209], v185 offset:26624
	ds_read_b64_tr_b16 v[210:211], v185 offset:27136
	ds_read_b64_tr_b16 v[212:213], v185 offset:30720
	ds_read_b64_tr_b16 v[214:215], v185 offset:31232
	v_max_f32_e32 v65, v183, v207
	v_mov_b32_e32 v183, v65
	s_mov_b32 s12, 0xc3160000
	s_nop 0
	v_permlane32_swap_b32_e32 v65, v183
	s_mov_b32 s13, 0x41000000
	v_max_f32_e32 v65, v65, v183
	s_nop 0
	v_cmp_gt_f32_e32 vcc, s12, v65
	s_cmp_lg_u64 vcc, exec
	s_cselect_b64 s[18:19], -1, 0
	s_cmp_eq_u64 vcc, exec
	s_cbranch_scc1 .Lc_pvB_skip
	v_cmp_lt_f32_e32 vcc, s13, v65
	s_cbranch_vccnz .Lc_pvB_resc
	s_waitcnt lgkmcnt(14)
	v_mfma_f32_32x32x16_bf16 v[48:63], v[86:89], v[168:171], v[48:63]
	v_exp_f32_e32 v128, v128
	v_exp_f32_e32 v129, v129
	s_waitcnt lgkmcnt(12)
	v_mfma_f32_32x32x16_bf16 v[32:47], v[108:111], v[168:171], v[32:47]
	v_exp_f32_e32 v130, v130
	v_exp_f32_e32 v131, v131
	v_pk_add_f32 v[82:83], v[128:129], 0 op_sel_hi:[1,0]
	s_waitcnt lgkmcnt(10)
	v_mfma_f32_32x32x16_bf16 v[16:31], v[104:107], v[168:171], v[16:31]
	v_exp_f32_e32 v132, v132
	v_exp_f32_e32 v133, v133
	v_pk_add_f32 v[82:83], v[130:131], v[82:83]
	v_cvt_pk_bf16_f32 v172, v128, v129
	s_waitcnt lgkmcnt(8)
	v_mfma_f32_32x32x16_bf16 v[0:15], v[90:93], v[168:171], v[0:15]
	v_exp_f32_e32 v134, v134
	v_exp_f32_e32 v135, v135
	v_pk_add_f32 v[82:83], v[132:133], v[82:83]
	v_cvt_pk_bf16_f32 v173, v130, v131
	ds_read_b64_tr_b16 v[74:75], v185 offset:19456
	ds_read_b64_tr_b16 v[76:77], v185 offset:19968
	ds_read_b64_tr_b16 v[78:79], v185 offset:23552
	ds_read_b64_tr_b16 v[80:81], v185 offset:24064
	ds_read_b64_tr_b16 v[94:95], v185 offset:27648
	ds_read_b64_tr_b16 v[96:97], v185 offset:28160
	ds_read_b64_tr_b16 v[216:217], v185 offset:31744
	ds_read_b64_tr_b16 v[218:219], v185 offset:32256
	s_waitcnt lgkmcnt(14)
	v_mfma_f32_32x32x16_bf16 v[48:63], v[66:69], v[160:163], v[48:63]
	v_exp_f32_e32 v136, v136
	v_exp_f32_e32 v137, v137
	v_pk_add_f32 v[82:83], v[134:135], v[82:83]
	v_cvt_pk_bf16_f32 v174, v132, v133
	s_waitcnt lgkmcnt(12)
	v_mfma_f32_32x32x16_bf16 v[32:47], v[70:73], v[160:163], v[32:47]
	v_exp_f32_e32 v138, v138
	v_exp_f32_e32 v139, v139
	v_pk_add_f32 v[82:83], v[136:137], v[82:83]
	v_cvt_pk_bf16_f32 v175, v134, v135
	s_waitcnt lgkmcnt(10)
	v_mfma_f32_32x32x16_bf16 v[16:31], v[208:211], v[160:163], v[16:31]
	v_exp_f32_e32 v140, v140
	v_exp_f32_e32 v141, v141
	v_pk_add_f32 v[82:83], v[138:139], v[82:83]
	v_cvt_pk_bf16_f32 v168, v136, v137
	s_waitcnt lgkmcnt(8)
	v_mfma_f32_32x32x16_bf16 v[0:15], v[212:215], v[160:163], v[0:15]
	v_exp_f32_e32 v142, v142
	v_exp_f32_e32 v143, v143
	v_pk_add_f32 v[82:83], v[140:141], v[82:83]
	v_cvt_pk_bf16_f32 v169, v138, v139
	s_waitcnt lgkmcnt(6)
	v_mfma_f32_32x32x16_bf16 v[48:63], v[74:77], v[164:167], v[48:63]
	v_exp_f32_e32 v112, v112
	v_exp_f32_e32 v113, v113
	v_pk_add_f32 v[82:83], v[142:143], v[82:83]
	v_cvt_pk_bf16_f32 v170, v140, v141
	s_waitcnt lgkmcnt(4)
	v_mfma_f32_32x32x16_bf16 v[32:47], v[78:81], v[164:167], v[32:47]
	v_exp_f32_e32 v114, v114
	v_exp_f32_e32 v115, v115
	v_pk_add_f32 v[82:83], v[112:113], v[82:83]
	v_cvt_pk_bf16_f32 v171, v142, v143
	s_waitcnt lgkmcnt(2)
	v_mfma_f32_32x32x16_bf16 v[16:31], v[94:97], v[164:167], v[16:31]
	v_exp_f32_e32 v116, v116
	v_exp_f32_e32 v117, v117
	v_pk_add_f32 v[82:83], v[114:115], v[82:83]
	v_cvt_pk_bf16_f32 v160, v112, v113
	s_waitcnt lgkmcnt(0)
	v_mfma_f32_32x32x16_bf16 v[0:15], v[216:219], v[164:167], v[0:15]
	v_exp_f32_e32 v118, v118
	v_exp_f32_e32 v119, v119
	v_pk_add_f32 v[82:83], v[116:117], v[82:83]
	v_cvt_pk_bf16_f32 v161, v114, v115
	v_exp_f32_e32 v120, v120
	v_exp_f32_e32 v121, v121
	v_pk_add_f32 v[82:83], v[118:119], v[82:83]
	v_cvt_pk_bf16_f32 v162, v116, v117
	v_exp_f32_e32 v122, v122
	v_exp_f32_e32 v123, v123
	v_pk_add_f32 v[82:83], v[120:121], v[82:83]
	v_cvt_pk_bf16_f32 v163, v118, v119
	v_exp_f32_e32 v124, v124
	v_exp_f32_e32 v125, v125
	v_pk_add_f32 v[82:83], v[122:123], v[82:83]
	v_cvt_pk_bf16_f32 v164, v120, v121
	v_exp_f32_e32 v126, v126
	v_exp_f32_e32 v127, v127
	v_pk_add_f32 v[82:83], v[124:125], v[82:83]
	v_cvt_pk_bf16_f32 v165, v122, v123
	v_pk_add_f32 v[82:83], v[126:127], v[82:83]
	v_cvt_pk_bf16_f32 v166, v124, v125
	v_cvt_pk_bf16_f32 v167, v126, v127
	v_add_f32_e32 v82, v82, v83
	s_nop 0
	v_add_f32_e32 v205, v205, v82
	s_branch .LBB0_199
; #define PV_RD(ST, SET) do { _Pragma("unroll") for (int db = 0; db < 4; ++db) { const LAS char* p = vt + (db * 4 + (ST)) * 1024; vlo[SET][db] = vtr(p); vhi[SET][db] = vtr(p + 512); } } while (0)
; #define PV_MM(ST, SET) do { _Pragma("unroll") for (int db = 0; db < 4; ++db) { const bf16x8 vf = {vlo[SET][db][0], vlo[SET][db][1], vlo[SET][db][2], vlo[SET][db][3], vhi[SET][db][0], vhi[SET][db][1], vhi[SET][db][2], vhi[SET][db][3]}; \
;                         o[db] = __builtin_amdgcn_mfma_f32_32x32x16_bf16(vf, pf[ST], o[db], 0, 0, 0); } } while (0)
; #define PV_RD(ST, SET) do { _Pragma("unroll") for (int db = 0; db < 4; ++db) { const LAS char* p = vt + (db * 4 + (ST)) * 1024; vlo[SET][db] = vtr(p); vhi[SET][db] = vtr(p + 512); } } while (0)
; #define PV_MM(ST, SET) do { _Pragma("unroll") for (int db = 0; db < 4; ++db) { const bf16x8 vf = {vlo[SET][db][0], vlo[SET][db][1], vlo[SET][db][2], vlo[SET][db][3], vhi[SET][db][0], vhi[SET][db][1], vhi[SET][db][2], vhi[SET][db][3]}; \
;                         o[db] = __builtin_amdgcn_mfma_f32_32x32x16_bf16(vf, pf[ST], o[db], 0, 0, 0); } } while (0)
; __device__ __forceinline__ void attn_C_item(const bf16_t* P, bf16_t* act_c, int S, int seqbase, int q0, int h, float lam, float oml, const float* subln_g, LAS char* lds, int tid, int w, int lane) {
;     ...
;             __builtin_amdgcn_sched_barrier(0);
;             PV_RD(0, 0); PV_RD(1, 1);
;             C_BIASMAX(T);
;             PV_MM(0, 0); PV_RD(2, 0); PV_MM(1, 1); PV_RD(3, 1); PV_MM(2, 0); PV_MM(3, 1);
.Lc_pvB_skip:
	s_waitcnt lgkmcnt(14)
	v_mfma_f32_32x32x16_bf16 v[48:63], v[86:89], v[168:171], v[48:63]
	s_waitcnt lgkmcnt(12)
	v_mfma_f32_32x32x16_bf16 v[32:47], v[108:111], v[168:171], v[32:47]
	s_waitcnt lgkmcnt(10)
	v_mfma_f32_32x32x16_bf16 v[16:31], v[104:107], v[168:171], v[16:31]
	s_waitcnt lgkmcnt(8)
	v_mfma_f32_32x32x16_bf16 v[0:15], v[90:93], v[168:171], v[0:15]
	ds_read_b64_tr_b16 v[74:75], v185 offset:19456
	ds_read_b64_tr_b16 v[76:77], v185 offset:19968
	ds_read_b64_tr_b16 v[78:79], v185 offset:23552
	ds_read_b64_tr_b16 v[80:81], v185 offset:24064
	ds_read_b64_tr_b16 v[94:95], v185 offset:27648
	ds_read_b64_tr_b16 v[96:97], v185 offset:28160
	ds_read_b64_tr_b16 v[216:217], v185 offset:31744
	ds_read_b64_tr_b16 v[218:219], v185 offset:32256
	s_waitcnt lgkmcnt(14)
	v_mfma_f32_32x32x16_bf16 v[48:63], v[66:69], v[160:163], v[48:63]
	s_waitcnt lgkmcnt(12)
	v_mfma_f32_32x32x16_bf16 v[32:47], v[70:73], v[160:163], v[32:47]
	s_waitcnt lgkmcnt(10)
	v_mfma_f32_32x32x16_bf16 v[16:31], v[208:211], v[160:163], v[16:31]
	s_waitcnt lgkmcnt(8)
	v_mfma_f32_32x32x16_bf16 v[0:15], v[212:215], v[160:163], v[0:15]
	s_waitcnt lgkmcnt(6)
	v_mfma_f32_32x32x16_bf16 v[48:63], v[74:77], v[164:167], v[48:63]
	s_waitcnt lgkmcnt(4)
	v_mfma_f32_32x32x16_bf16 v[32:47], v[78:81], v[164:167], v[32:47]
	s_waitcnt lgkmcnt(2)
	v_mfma_f32_32x32x16_bf16 v[16:31], v[94:97], v[164:167], v[16:31]
	s_waitcnt lgkmcnt(0)
	v_mfma_f32_32x32x16_bf16 v[0:15], v[216:219], v[164:167], v[0:15]
	s_branch .LBB0_199
.Lc_pvB_resc:
	s_waitcnt lgkmcnt(14)
	v_mfma_f32_32x32x16_bf16 v[48:63], v[86:89], v[168:171], v[48:63]
	s_waitcnt lgkmcnt(12)
	v_mfma_f32_32x32x16_bf16 v[32:47], v[108:111], v[168:171], v[32:47]
	s_waitcnt lgkmcnt(10)
	v_mfma_f32_32x32x16_bf16 v[16:31], v[104:107], v[168:171], v[16:31]
	s_waitcnt lgkmcnt(8)
	v_mfma_f32_32x32x16_bf16 v[0:15], v[90:93], v[168:171], v[0:15]
	ds_read_b64_tr_b16 v[74:75], v185 offset:19456
	ds_read_b64_tr_b16 v[76:77], v185 offset:19968
	ds_read_b64_tr_b16 v[78:79], v185 offset:23552
	ds_read_b64_tr_b16 v[80:81], v185 offset:24064
	ds_read_b64_tr_b16 v[94:95], v185 offset:27648
	ds_read_b64_tr_b16 v[96:97], v185 offset:28160
	ds_read_b64_tr_b16 v[216:217], v185 offset:31744
	ds_read_b64_tr_b16 v[218:219], v185 offset:32256
	s_waitcnt lgkmcnt(14)
	v_mfma_f32_32x32x16_bf16 v[48:63], v[66:69], v[160:163], v[48:63]
	s_waitcnt lgkmcnt(12)
	v_mfma_f32_32x32x16_bf16 v[32:47], v[70:73], v[160:163], v[32:47]
	s_waitcnt lgkmcnt(10)
	v_mfma_f32_32x32x16_bf16 v[16:31], v[208:211], v[160:163], v[16:31]
	s_waitcnt lgkmcnt(8)
	v_mfma_f32_32x32x16_bf16 v[0:15], v[212:215], v[160:163], v[0:15]
	s_waitcnt lgkmcnt(6)
	v_mfma_f32_32x32x16_bf16 v[48:63], v[74:77], v[164:167], v[48:63]
	s_waitcnt lgkmcnt(4)
	v_mfma_f32_32x32x16_bf16 v[32:47], v[78:81], v[164:167], v[32:47]
	s_waitcnt lgkmcnt(2)
	v_mfma_f32_32x32x16_bf16 v[16:31], v[94:97], v[164:167], v[16:31]
	s_waitcnt lgkmcnt(0)
	v_mfma_f32_32x32x16_bf16 v[0:15], v[216:219], v[164:167], v[0:15]
	v_mov_b32_e32 v80, v65
	s_branch .Lc_resc
